# grid barrier: XCD leader issues its cache invalidate right after its L2 writeback completes (all local workgroups have arrived, nothing can refill the caches), so it completes under the cross-XCD wait
# speedup vs baseline: 1.0089x; 1.0004x over previous
.LBB0_1168:
	s_andn2_saveexec_b64 s[20:21], s[20:21]
	s_cbranch_execz .LBB0_1188
	s_mov_b64 s[20:21], exec
	buffer_wbl2 sc1
	s_waitcnt lgkmcnt(0)
	s_waitcnt vmcnt(0)
	buffer_inv sc1
	v_mbcnt_lo_u32_b32 v0, s20, 0
	v_mbcnt_hi_u32_b32 v0, s21, v0
	v_cmp_eq_u32_e32 vcc, 0, v0
	s_and_saveexec_b64 s[22:23], vcc
	s_cbranch_execz .LBB0_1171
	s_bcnt1_i32_b64 s20, s[20:21]
	v_readlane_b32 s4, v253, 2
	v_mov_b32_e32 v3, s20
	v_readlane_b32 s5, v253, 3
	s_nop 4
	global_atomic_add v3, v1, v3, s[4:5] sc0

.LBB0_1185:
	s_or_b64 exec, exec, s[20:21]
	s_mov_b64 s[20:21], exec
	v_mbcnt_lo_u32_b32 v0, s20, 0
	v_mbcnt_hi_u32_b32 v0, s21, v0
	v_cmp_eq_u32_e32 vcc, 0, v0
	s_waitcnt vmcnt(0)
	s_and_saveexec_b64 s[22:23], vcc
	s_cbranch_execz .LBB0_1187
	s_bcnt1_i32_b64 s20, s[20:21]
	v_readlane_b32 s4, v253, 0
	v_mov_b32_e32 v0, s20
	v_readlane_b32 s5, v253, 1
	s_nop 4
	global_atomic_add v1, v0, s[4:5]
